# grid barrier: the XCD leader releases its XCD before its own L1 invalidate (5 seams)
# speedup vs baseline: 1.0018x; 1.0018x over previous
.LBB0_255:
	s_or_b64 exec, exec, s[4:5]
	s_mov_b64 s[4:5], exec
	v_mbcnt_lo_u32_b32 v1, s4, 0
	v_mbcnt_hi_u32_b32 v1, s5, v1
	v_cmp_eq_u32_e32 vcc, 0, v1
	s_waitcnt vmcnt(0)
	s_and_saveexec_b64 s[6:7], vcc
	s_cbranch_execz .LBB0_257
	s_bcnt1_i32_b64 s4, s[4:5]
	v_mov_b32_e32 v1, 0x2000
	v_mov_b32_e32 v2, s4
	global_atomic_add v1, v2, s[2:3] offset:1024
.LBB0_257:
	s_or_b64 exec, exec, s[6:7]
	buffer_inv sc1
	s_waitcnt vmcnt(0)
